# S5 scans: s5_pass1 loop pipelined the same way as s5_pass2 (B.u chains one iteration ahead of the recurrence), counted lgkmcnt for the in-place u reloads
# baseline (speedup 1.0000x reference)
; __device__ __forceinline__ void s5_pass1(const Params& p, int layer, int task, char* sm) {
;     ...
; #pragma unroll
;   for (int h = 0; h < 16; h++) { B2[h].x = p.SB[pi * 32 + h]; B2[h].y = p.SB[pi * 32 + 16 + h]; }
;   const float ar = p.SA[pi * 4], ai = p.SA[pi * 4 + 1];
;   float sr = 0.f, si = 0.f;
;   __builtin_amdgcn_wave_barrier();
;   for (int l = 0; l < 128; l++) S5_STEP(sU + l * 16)
.LBB0_477:
	v_mov_b32_e32 v37, v38
	v_add_u32_e32 v60, s2, v41
	ds_read_b128 v[42:45], v60
	ds_read_b128 v[46:49], v60 offset:16
	ds_read_b128 v[50:53], v60 offset:32
	ds_read_b128 v[54:57], v60 offset:48
	ds_read_b128 v[108:111], v60 offset:64
	ds_read_b128 v[112:115], v60 offset:80
	ds_read_b128 v[116:119], v60 offset:96
	ds_read_b128 v[120:123], v60 offset:112
	s_waitcnt lgkmcnt(0)
	v_pk_mul_f32 v[128:129], v[12:13], v[42:43] op_sel:[0,1]
	v_pk_mul_f32 v[130:131], v[12:13], v[108:109] op_sel:[0,1]
	v_pk_fma_f32 v[128:129], v[16:17], v[42:43], v[128:129] op_sel_hi:[1,0,1]
	v_pk_fma_f32 v[130:131], v[16:17], v[108:109], v[130:131] op_sel_hi:[1,0,1]
	v_pk_fma_f32 v[128:129], v[18:19], v[44:45], v[128:129] op_sel_hi:[1,0,1]
	v_pk_fma_f32 v[130:131], v[18:19], v[110:111], v[130:131] op_sel_hi:[1,0,1]
	v_pk_fma_f32 v[128:129], v[14:15], v[44:45], v[128:129] op_sel:[0,1,0]
	v_pk_fma_f32 v[130:131], v[14:15], v[110:111], v[130:131] op_sel:[0,1,0]
	ds_read_b128 v[42:45], v60 offset:128
	ds_read_b128 v[108:111], v60 offset:192
	v_pk_fma_f32 v[128:129], v[20:21], v[46:47], v[128:129] op_sel_hi:[1,0,1]
	v_pk_fma_f32 v[130:131], v[20:21], v[112:113], v[130:131] op_sel_hi:[1,0,1]
	v_pk_fma_f32 v[128:129], v[8:9], v[46:47], v[128:129] op_sel:[0,1,0]
	v_pk_fma_f32 v[130:131], v[8:9], v[112:113], v[130:131] op_sel:[0,1,0]
	v_pk_fma_f32 v[128:129], v[22:23], v[48:49], v[128:129] op_sel_hi:[1,0,1]
	v_pk_fma_f32 v[130:131], v[22:23], v[114:115], v[130:131] op_sel_hi:[1,0,1]
	v_pk_fma_f32 v[128:129], v[10:11], v[48:49], v[128:129] op_sel:[0,1,0]
	v_pk_fma_f32 v[130:131], v[10:11], v[114:115], v[130:131] op_sel:[0,1,0]
	ds_read_b128 v[46:49], v60 offset:144
	ds_read_b128 v[112:115], v60 offset:208
	v_pk_fma_f32 v[128:129], v[24:25], v[50:51], v[128:129] op_sel_hi:[1,0,1]
	v_pk_fma_f32 v[130:131], v[24:25], v[116:117], v[130:131] op_sel_hi:[1,0,1]
	v_pk_fma_f32 v[128:129], v[4:5], v[50:51], v[128:129] op_sel:[0,1,0]
	v_pk_fma_f32 v[130:131], v[4:5], v[116:117], v[130:131] op_sel:[0,1,0]
	v_pk_fma_f32 v[128:129], v[26:27], v[52:53], v[128:129] op_sel_hi:[1,0,1]
	v_pk_fma_f32 v[130:131], v[26:27], v[118:119], v[130:131] op_sel_hi:[1,0,1]
	v_pk_fma_f32 v[128:129], v[6:7], v[52:53], v[128:129] op_sel:[0,1,0]
	v_pk_fma_f32 v[130:131], v[6:7], v[118:119], v[130:131] op_sel:[0,1,0]
	ds_read_b128 v[50:53], v60 offset:160
	ds_read_b128 v[116:119], v60 offset:224
	v_pk_fma_f32 v[128:129], v[28:29], v[54:55], v[128:129] op_sel_hi:[1,0,1]
	v_pk_fma_f32 v[130:131], v[28:29], v[120:121], v[130:131] op_sel_hi:[1,0,1]
	v_pk_fma_f32 v[128:129], v[0:1], v[54:55], v[128:129] op_sel:[0,1,0]
	v_pk_fma_f32 v[130:131], v[0:1], v[120:121], v[130:131] op_sel:[0,1,0]
	v_pk_fma_f32 v[128:129], v[30:31], v[56:57], v[128:129] op_sel_hi:[1,0,1]
	v_pk_fma_f32 v[130:131], v[30:31], v[122:123], v[130:131] op_sel_hi:[1,0,1]
	v_pk_fma_f32 v[128:129], v[2:3], v[56:57], v[128:129] op_sel:[0,1,0]
	v_pk_fma_f32 v[130:131], v[2:3], v[122:123], v[130:131] op_sel:[0,1,0]
	ds_read_b128 v[54:57], v60 offset:176
	ds_read_b128 v[120:123], v60 offset:240
	s_waitcnt lgkmcnt(0)
; __device__ __forceinline__ void s5_pass1(const Params& p, int layer, int task, char* sm) {
;     ...
;   for (int l = 0; l < 128; l++) S5_STEP(sU + l * 16)
;   *(float2*)(p.END + (((size_t)(b * 128 + c) * 32 + g) * 64 + lane) * 2) = make_float2(sr, si);
.Ls5scan_p1:
	v_add_u32_e32 v60, s2, v41
	s_waitcnt lgkmcnt(6)
	v_pk_mul_f32 v[124:125], v[12:13], v[42:43] op_sel:[0,1]
	v_pk_mul_f32 v[126:127], v[12:13], v[108:109] op_sel:[0,1]
	v_pk_mul_f32 v[134:135], v[34:35], v[36:37] op_sel:[0,1]
	v_pk_fma_f32 v[124:125], v[16:17], v[42:43], v[124:125] op_sel_hi:[1,0,1]
	v_pk_fma_f32 v[126:127], v[16:17], v[108:109], v[126:127] op_sel_hi:[1,0,1]
	v_pk_fma_f32 v[136:137], v[32:33], v[36:37], v[134:135] neg_lo:[0,0,1] neg_hi:[0,0,1]
	v_pk_fma_f32 v[124:125], v[18:19], v[44:45], v[124:125] op_sel_hi:[1,0,1]
	v_pk_fma_f32 v[126:127], v[18:19], v[110:111], v[126:127] op_sel_hi:[1,0,1]
	v_pk_fma_f32 v[138:139], v[32:33], v[36:37], v[134:135] op_sel_hi:[1,0,1]
	v_pk_fma_f32 v[124:125], v[14:15], v[44:45], v[124:125] op_sel:[0,1,0]
	v_pk_fma_f32 v[126:127], v[14:15], v[110:111], v[126:127] op_sel:[0,1,0]
	v_mov_b32_e32 v137, v139
	ds_read_b128 v[42:45], v60 offset:256
	ds_read_b128 v[108:111], v60 offset:320
	s_waitcnt lgkmcnt(6)
	v_pk_fma_f32 v[124:125], v[20:21], v[46:47], v[124:125] op_sel_hi:[1,0,1]
	v_pk_fma_f32 v[126:127], v[20:21], v[112:113], v[126:127] op_sel_hi:[1,0,1]
	v_pk_add_f32 v[132:133], v[136:137], v[128:129]
	v_pk_fma_f32 v[124:125], v[8:9], v[46:47], v[124:125] op_sel:[0,1,0]
	v_pk_fma_f32 v[126:127], v[8:9], v[112:113], v[126:127] op_sel:[0,1,0]
	v_pk_mul_f32 v[134:135], v[34:35], v[132:133] op_sel:[0,1]
	v_pk_fma_f32 v[124:125], v[22:23], v[48:49], v[124:125] op_sel_hi:[1,0,1]
	v_pk_fma_f32 v[126:127], v[22:23], v[114:115], v[126:127] op_sel_hi:[1,0,1]
	v_pk_fma_f32 v[136:137], v[32:33], v[132:133], v[134:135] neg_lo:[0,0,1] neg_hi:[0,0,1]
	v_pk_fma_f32 v[124:125], v[10:11], v[48:49], v[124:125] op_sel:[0,1,0]
	v_pk_fma_f32 v[126:127], v[10:11], v[114:115], v[126:127] op_sel:[0,1,0]
	v_pk_fma_f32 v[138:139], v[32:33], v[132:133], v[134:135] op_sel_hi:[1,0,1]
	ds_read_b128 v[46:49], v60 offset:272
	ds_read_b128 v[112:115], v60 offset:336
	s_waitcnt lgkmcnt(6)
	v_pk_fma_f32 v[124:125], v[24:25], v[50:51], v[124:125] op_sel_hi:[1,0,1]
	v_pk_fma_f32 v[126:127], v[24:25], v[116:117], v[126:127] op_sel_hi:[1,0,1]
	v_mov_b32_e32 v137, v139
	v_pk_fma_f32 v[124:125], v[4:5], v[50:51], v[124:125] op_sel:[0,1,0]
	v_pk_fma_f32 v[126:127], v[4:5], v[116:117], v[126:127] op_sel:[0,1,0]
	v_pk_add_f32 v[36:37], v[136:137], v[130:131]
	v_pk_fma_f32 v[124:125], v[26:27], v[52:53], v[124:125] op_sel_hi:[1,0,1]
	v_pk_fma_f32 v[126:127], v[26:27], v[118:119], v[126:127] op_sel_hi:[1,0,1]
	v_pk_fma_f32 v[124:125], v[6:7], v[52:53], v[124:125] op_sel:[0,1,0]
	v_pk_fma_f32 v[126:127], v[6:7], v[118:119], v[126:127] op_sel:[0,1,0]
	ds_read_b128 v[50:53], v60 offset:288
	ds_read_b128 v[116:119], v60 offset:352
	s_waitcnt lgkmcnt(6)
	v_pk_fma_f32 v[124:125], v[28:29], v[54:55], v[124:125] op_sel_hi:[1,0,1]
	v_pk_fma_f32 v[126:127], v[28:29], v[120:121], v[126:127] op_sel_hi:[1,0,1]
	v_pk_fma_f32 v[124:125], v[0:1], v[54:55], v[124:125] op_sel:[0,1,0]
	v_pk_fma_f32 v[126:127], v[0:1], v[120:121], v[126:127] op_sel:[0,1,0]
	v_pk_fma_f32 v[124:125], v[30:31], v[56:57], v[124:125] op_sel_hi:[1,0,1]
	v_pk_fma_f32 v[126:127], v[30:31], v[122:123], v[126:127] op_sel_hi:[1,0,1]
	v_pk_fma_f32 v[124:125], v[2:3], v[56:57], v[124:125] op_sel:[0,1,0]
	v_pk_fma_f32 v[126:127], v[2:3], v[122:123], v[126:127] op_sel:[0,1,0]
	ds_read_b128 v[54:57], v60 offset:304
	ds_read_b128 v[120:123], v60 offset:368
	s_addk_i32 s2, 0x80
	v_mov_b64_e32 v[128:129], v[124:125]
	v_mov_b64_e32 v[130:131], v[126:127]
	s_cmpk_eq_i32 s2, 0x1f80
	s_cbranch_scc0 .Ls5scan_p1
	v_pk_mul_f32 v[134:135], v[34:35], v[36:37] op_sel:[0,1]
	s_nop 0
	v_pk_fma_f32 v[136:137], v[32:33], v[36:37], v[134:135] neg_lo:[0,0,1] neg_hi:[0,0,1]
	s_nop 0
	v_pk_fma_f32 v[138:139], v[32:33], v[36:37], v[134:135] op_sel_hi:[1,0,1]
	s_nop 0
	v_mov_b32_e32 v137, v139
	s_nop 0
	v_pk_add_f32 v[132:133], v[136:137], v[128:129]
	s_nop 0
	v_pk_mul_f32 v[134:135], v[34:35], v[132:133] op_sel:[0,1]
	s_nop 0
	v_pk_fma_f32 v[136:137], v[32:33], v[132:133], v[134:135] neg_lo:[0,0,1] neg_hi:[0,0,1]
	s_nop 0
	v_pk_fma_f32 v[138:139], v[32:33], v[132:133], v[134:135] op_sel_hi:[1,0,1]
	s_nop 0
	v_mov_b32_e32 v137, v139
	s_nop 0
	v_pk_add_f32 v[36:37], v[136:137], v[130:131]
	s_nop 0
	s_waitcnt lgkmcnt(0)
	v_mov_b32_e32 v38, v37
	s_lshl_b32 s1, s1, 12
	s_lshl_b32 s0, s0, 5
	s_or_b32 s0, s0, s1
	v_or_b32_e32 v0, s0, v40
	v_lshlrev_b32_e32 v1, 1, v39
	v_readlane_b32 s0, v253, 38
	v_lshl_or_b32 v144, v0, 7, v1
	v_readlane_b32 s1, v253, 39
	v_readlane_b32 s2, v253, 40
	v_readlane_b32 s3, v253, 41
	v_lshl_add_u64 v[0:1], v[144:145], 2, s[0:1]
	v_readlane_b32 s4, v253, 42
	v_readlane_b32 s5, v253, 43
	v_readlane_b32 s6, v253, 44
	v_readlane_b32 s7, v253, 45
	global_store_dwordx2 v[0:1], v[36:37], off

; __device__ __forceinline__ bf f2bf(float f) { return (bf)(pk2(f, 0.f) & 0xFFFFu); }
; __device__ __forceinline__ void s5_pass2(const Params& p, int layer, int task, char* sm) {
;     ...
;       for (int l = 0; l < 32; l++) {
;         S5_STEP(sU + l * 16)
;         sS[l * 136 + lane] = f2bf(sr); sS[l * 136 + 64 + lane] = f2bf(si);
;       }
.LBB0_1796:
	v_add_u32_e32 v41, s9, v79
	ds_read_b128 v[104:107], v41
	ds_read_b128 v[108:111], v41 offset:16
	ds_read_b128 v[112:115], v41 offset:32
	ds_read_b128 v[116:119], v41 offset:48
	ds_read_b128 v[120:123], v41 offset:64
	ds_read_b128 v[124:127], v41 offset:80
	ds_read_b128 v[128:131], v41 offset:96
	ds_read_b128 v[132:135], v41 offset:112
	s_waitcnt lgkmcnt(0)
	v_pk_mul_f32 v[140:141], v[20:21], v[104:105] op_sel:[0,1]
	v_pk_mul_f32 v[142:143], v[20:21], v[120:121] op_sel:[0,1]
	v_pk_fma_f32 v[140:141], v[52:53], v[104:105], v[140:141] op_sel_hi:[1,0,1]
	v_pk_fma_f32 v[142:143], v[52:53], v[120:121], v[142:143] op_sel_hi:[1,0,1]
	v_pk_fma_f32 v[140:141], v[54:55], v[106:107], v[140:141] op_sel_hi:[1,0,1]
	v_pk_fma_f32 v[142:143], v[54:55], v[122:123], v[142:143] op_sel_hi:[1,0,1]
	v_pk_fma_f32 v[140:141], v[22:23], v[106:107], v[140:141] op_sel:[0,1,0]
	v_pk_fma_f32 v[142:143], v[22:23], v[122:123], v[142:143] op_sel:[0,1,0]
	ds_read_b128 v[104:107], v41 offset:128
	ds_read_b128 v[120:123], v41 offset:192
	v_pk_fma_f32 v[140:141], v[56:57], v[108:109], v[140:141] op_sel_hi:[1,0,1]
	v_pk_fma_f32 v[142:143], v[56:57], v[124:125], v[142:143] op_sel_hi:[1,0,1]
	v_pk_fma_f32 v[140:141], v[16:17], v[108:109], v[140:141] op_sel:[0,1,0]
	v_pk_fma_f32 v[142:143], v[16:17], v[124:125], v[142:143] op_sel:[0,1,0]
	v_pk_fma_f32 v[140:141], v[58:59], v[110:111], v[140:141] op_sel_hi:[1,0,1]
	v_pk_fma_f32 v[142:143], v[58:59], v[126:127], v[142:143] op_sel_hi:[1,0,1]
	v_pk_fma_f32 v[140:141], v[18:19], v[110:111], v[140:141] op_sel:[0,1,0]
	v_pk_fma_f32 v[142:143], v[18:19], v[126:127], v[142:143] op_sel:[0,1,0]
	ds_read_b128 v[108:111], v41 offset:144
	ds_read_b128 v[124:127], v41 offset:208
	v_pk_fma_f32 v[140:141], v[60:61], v[112:113], v[140:141] op_sel_hi:[1,0,1]
	v_pk_fma_f32 v[142:143], v[60:61], v[128:129], v[142:143] op_sel_hi:[1,0,1]
	v_pk_fma_f32 v[140:141], v[12:13], v[112:113], v[140:141] op_sel:[0,1,0]
	v_pk_fma_f32 v[142:143], v[12:13], v[128:129], v[142:143] op_sel:[0,1,0]
	v_pk_fma_f32 v[140:141], v[62:63], v[114:115], v[140:141] op_sel_hi:[1,0,1]
	v_pk_fma_f32 v[142:143], v[62:63], v[130:131], v[142:143] op_sel_hi:[1,0,1]
	v_pk_fma_f32 v[140:141], v[14:15], v[114:115], v[140:141] op_sel:[0,1,0]
	v_pk_fma_f32 v[142:143], v[14:15], v[130:131], v[142:143] op_sel:[0,1,0]
	ds_read_b128 v[112:115], v41 offset:160
	ds_read_b128 v[128:131], v41 offset:224
	v_pk_fma_f32 v[140:141], v[64:65], v[116:117], v[140:141] op_sel_hi:[1,0,1]
	v_pk_fma_f32 v[142:143], v[64:65], v[132:133], v[142:143] op_sel_hi:[1,0,1]
	v_pk_fma_f32 v[140:141], v[8:9], v[116:117], v[140:141] op_sel:[0,1,0]
	v_pk_fma_f32 v[142:143], v[8:9], v[132:133], v[142:143] op_sel:[0,1,0]
	v_pk_fma_f32 v[140:141], v[66:67], v[118:119], v[140:141] op_sel_hi:[1,0,1]
	v_pk_fma_f32 v[142:143], v[66:67], v[134:135], v[142:143] op_sel_hi:[1,0,1]
	v_pk_fma_f32 v[140:141], v[10:11], v[118:119], v[140:141] op_sel:[0,1,0]
	v_pk_fma_f32 v[142:143], v[10:11], v[134:135], v[142:143] op_sel:[0,1,0]
	ds_read_b128 v[116:119], v41 offset:176
	ds_read_b128 v[132:135], v41 offset:240
	s_waitcnt vmcnt(5)
	s_waitcnt lgkmcnt(0)
.Ls5scan_0:
	v_add_u32_e32 v41, s9, v79
	v_add_u32_e32 v103, v79, v40
	s_waitcnt lgkmcnt(10)
	v_pk_mul_f32 v[136:137], v[20:21], v[104:105] op_sel:[0,1]
	v_pk_mul_f32 v[138:139], v[20:21], v[120:121] op_sel:[0,1]
	v_pk_mul_f32 v[76:77], v[74:75], v[70:71] op_sel:[0,1]
	v_pk_fma_f32 v[136:137], v[52:53], v[104:105], v[136:137] op_sel_hi:[1,0,1]
	v_pk_fma_f32 v[138:139], v[52:53], v[120:121], v[138:139] op_sel_hi:[1,0,1]
	v_pk_fma_f32 v[146:147], v[68:69], v[70:71], v[76:77] neg_lo:[0,0,1] neg_hi:[0,0,1]
	v_pk_fma_f32 v[136:137], v[54:55], v[106:107], v[136:137] op_sel_hi:[1,0,1]
	v_pk_fma_f32 v[138:139], v[54:55], v[122:123], v[138:139] op_sel_hi:[1,0,1]
	v_pk_fma_f32 v[148:149], v[68:69], v[70:71], v[76:77] op_sel_hi:[1,0,1]
	v_pk_fma_f32 v[136:137], v[22:23], v[106:107], v[136:137] op_sel:[0,1,0]
	v_pk_fma_f32 v[138:139], v[22:23], v[122:123], v[138:139] op_sel:[0,1,0]
	v_mov_b32_e32 v147, v149
	ds_read_b128 v[104:107], v41 offset:256
	ds_read_b128 v[120:123], v41 offset:320
	s_waitcnt lgkmcnt(8)
	v_pk_fma_f32 v[136:137], v[56:57], v[108:109], v[136:137] op_sel_hi:[1,0,1]
	v_pk_fma_f32 v[138:139], v[56:57], v[124:125], v[138:139] op_sel_hi:[1,0,1]
	v_pk_add_f32 v[42:43], v[146:147], v[140:141]
	v_pk_fma_f32 v[136:137], v[16:17], v[108:109], v[136:137] op_sel:[0,1,0]
	v_pk_fma_f32 v[138:139], v[16:17], v[124:125], v[138:139] op_sel:[0,1,0]
	v_cvt_pk_bf16_f32 v150, v42, s0
	ds_write_b16 v103, v150
	v_pk_fma_f32 v[136:137], v[58:59], v[110:111], v[136:137] op_sel_hi:[1,0,1]
	v_pk_fma_f32 v[138:139], v[58:59], v[126:127], v[138:139] op_sel_hi:[1,0,1]
	v_cvt_pk_bf16_f32 v151, v43, s0
	ds_write_b16 v103, v151 offset:128
	v_pk_fma_f32 v[136:137], v[18:19], v[110:111], v[136:137] op_sel:[0,1,0]
	v_pk_fma_f32 v[138:139], v[18:19], v[126:127], v[138:139] op_sel:[0,1,0]
	v_pk_mul_f32 v[76:77], v[74:75], v[42:43] op_sel:[0,1]
	ds_read_b128 v[108:111], v41 offset:272
	ds_read_b128 v[124:127], v41 offset:336
	s_waitcnt lgkmcnt(10)
	v_pk_fma_f32 v[136:137], v[60:61], v[112:113], v[136:137] op_sel_hi:[1,0,1]
	v_pk_fma_f32 v[138:139], v[60:61], v[128:129], v[138:139] op_sel_hi:[1,0,1]
	v_pk_fma_f32 v[146:147], v[68:69], v[42:43], v[76:77] neg_lo:[0,0,1] neg_hi:[0,0,1]
	v_pk_fma_f32 v[136:137], v[12:13], v[112:113], v[136:137] op_sel:[0,1,0]
	v_pk_fma_f32 v[138:139], v[12:13], v[128:129], v[138:139] op_sel:[0,1,0]
	v_pk_fma_f32 v[148:149], v[68:69], v[42:43], v[76:77] op_sel_hi:[1,0,1]
	v_pk_fma_f32 v[136:137], v[62:63], v[114:115], v[136:137] op_sel_hi:[1,0,1]
	v_pk_fma_f32 v[138:139], v[62:63], v[130:131], v[138:139] op_sel_hi:[1,0,1]
	v_mov_b32_e32 v147, v149
	v_pk_fma_f32 v[136:137], v[14:15], v[114:115], v[136:137] op_sel:[0,1,0]
	v_pk_fma_f32 v[138:139], v[14:15], v[130:131], v[138:139] op_sel:[0,1,0]
	v_pk_add_f32 v[70:71], v[146:147], v[142:143]
	ds_read_b128 v[112:115], v41 offset:288
	ds_read_b128 v[128:131], v41 offset:352
	s_waitcnt lgkmcnt(8)
	v_pk_fma_f32 v[136:137], v[64:65], v[116:117], v[136:137] op_sel_hi:[1,0,1]
	v_pk_fma_f32 v[138:139], v[64:65], v[132:133], v[138:139] op_sel_hi:[1,0,1]
	v_cvt_pk_bf16_f32 v150, v70, s0
	ds_write_b16 v103, v150 offset:272
	v_pk_fma_f32 v[136:137], v[8:9], v[116:117], v[136:137] op_sel:[0,1,0]
	v_pk_fma_f32 v[138:139], v[8:9], v[132:133], v[138:139] op_sel:[0,1,0]
	v_cvt_pk_bf16_f32 v151, v71, s0
	ds_write_b16 v103, v151 offset:400
	v_pk_fma_f32 v[136:137], v[66:67], v[118:119], v[136:137] op_sel_hi:[1,0,1]
	v_pk_fma_f32 v[138:139], v[66:67], v[134:135], v[138:139] op_sel_hi:[1,0,1]
	v_pk_fma_f32 v[136:137], v[10:11], v[118:119], v[136:137] op_sel:[0,1,0]
	v_pk_fma_f32 v[138:139], v[10:11], v[134:135], v[138:139] op_sel:[0,1,0]
	ds_read_b128 v[116:119], v41 offset:304
	ds_read_b128 v[132:135], v41 offset:368
	s_addk_i32 s9, 0x80
	v_add_u32_e32 v40, 0x220, v40
	v_mov_b64_e32 v[140:141], v[136:137]
	v_mov_b64_e32 v[142:143], v[138:139]
	s_cmpk_eq_i32 s9, 0x780
	s_cbranch_scc0 .Ls5scan_0
; __device__ __forceinline__ float ozero() { float z = 0.f; asm volatile("" : "+v"(z)); return z; }
; __device__ __forceinline__ bf f2bf(float f) { return (bf)(pk2(f, 0.f) & 0xFFFFu); }
; __device__ __forceinline__ f32x4 mfma16(bf16x8 a, bf16x8 b, f32x4 c) { return __builtin_amdgcn_mfma_f32_16x16x32_bf16(a, b, c, 0, 0, 0); }
; __device__ __forceinline__ void s5_pass2(const Params& p, int layer, int task, char* sm) {
;     ...
;       for (int l = 0; l < 32; l++) {
;         S5_STEP(sU + l * 16)
;         sS[l * 136 + lane] = f2bf(sr); sS[l * 136 + 64 + lane] = f2bf(si);
;       }
;       __builtin_amdgcn_wave_barrier();
; #pragma unroll
;       for (int mb = 0; mb < 2; mb++) {
;         const float z_ = ozero(); f32x4 acc = {z_, z_, z_, z_};
; #pragma unroll
;         for (int ks = 0; ks < 4; ks++) {
;           bf16x8 af = *(const bf16x8*)(sS + (16 * mb + (lane & 15)) * 136 + ks * 32 + 8 * (lane >> 4));
;           acc = mfma16(af, cf[ks], acc);
;         }
; #pragma unroll
;         for (int r = 0; r < 4; r++) {
;           const int l = 16 * mb + 4 * (lane >> 4) + r;
;           float y = acc[r] + dsk * sU[l * 16 + (lane & 15)];
;           p.YG[(tok0 + sub * 32 + l) * 512 + g * 16 + (lane & 15)] = f2bf(geluf_(y));
	v_add_u32_e32 v103, v79, v40
	v_pk_mul_f32 v[76:77], v[74:75], v[70:71] op_sel:[0,1]
	s_nop 0
	v_pk_fma_f32 v[146:147], v[68:69], v[70:71], v[76:77] neg_lo:[0,0,1] neg_hi:[0,0,1]
	s_nop 0
	v_pk_fma_f32 v[148:149], v[68:69], v[70:71], v[76:77] op_sel_hi:[1,0,1]
	s_nop 0
	v_mov_b32_e32 v147, v149
	s_nop 0
	v_pk_add_f32 v[42:43], v[146:147], v[140:141]
	s_nop 0
	v_cvt_pk_bf16_f32 v150, v42, s0
	s_nop 0
	ds_write_b16 v103, v150
	v_cvt_pk_bf16_f32 v151, v43, s0
	s_nop 0
	ds_write_b16 v103, v151 offset:128
	v_pk_mul_f32 v[76:77], v[74:75], v[42:43] op_sel:[0,1]
	s_nop 0
	v_pk_fma_f32 v[146:147], v[68:69], v[42:43], v[76:77] neg_lo:[0,0,1] neg_hi:[0,0,1]
	s_nop 0
	v_pk_fma_f32 v[148:149], v[68:69], v[42:43], v[76:77] op_sel_hi:[1,0,1]
	s_nop 0
	v_mov_b32_e32 v147, v149
	s_nop 0
	v_pk_add_f32 v[70:71], v[146:147], v[142:143]
	s_nop 0
	v_cvt_pk_bf16_f32 v150, v70, s0
	s_nop 0
	ds_write_b16 v103, v150 offset:272
	v_cvt_pk_bf16_f32 v151, v71, s0
	s_nop 0
	ds_write_b16 v103, v151 offset:400
	s_waitcnt lgkmcnt(0)
	v_mov_b32_e32 v40, v145
	ds_read_b128 v[104:107], v100 offset:2048
	ds_read_b32 v76, v83
	v_mov_b32_e32 v41, v40
	v_mov_b32_e32 v42, v40
	v_mov_b32_e32 v43, v40
	s_lshl_b32 s9, s11, 5
	v_mov_b32_e32 v77, s5
	s_cmp_eq_u32 s8, 4
	s_waitcnt vmcnt(4) lgkmcnt(1)
	v_mfma_f32_16x16x32_bf16 v[40:43], v[104:107], v[24:27], v[40:43]
	ds_read_b128 v[104:107], v100 offset:2112
	s_waitcnt vmcnt(3) lgkmcnt(0)
	v_mfma_f32_16x16x32_bf16 v[40:43], v[104:107], v[28:31], v[40:43]
	ds_read_b128 v[104:107], v100 offset:2176
	s_waitcnt vmcnt(2) lgkmcnt(0)
	v_mfma_f32_16x16x32_bf16 v[40:43], v[104:107], v[32:35], v[40:43]
	ds_read_b128 v[104:107], v100 offset:2240
	s_waitcnt vmcnt(1) lgkmcnt(0)
	v_mfma_f32_16x16x32_bf16 v[40:43], v[104:107], v[36:39], v[40:43]
	s_waitcnt vmcnt(0)
	s_nop 6
	v_fma_f32 v40, v102, v76, v40
	v_mul_f32_e32 v76, 0x3d372713, v40
	v_mul_f32_e32 v76, v40, v76
	v_fma_f32 v76, v40, v76, v40
	v_mul_f32_e32 v76, 0x3f4c422a, v76
	v_add_f32_e32 v76, v76, v76
	v_mul_f32_e32 v76, 0x3fb8aa3b, v76
	v_exp_f32_e32 v76, v76
	v_mul_f32_e32 v40, 0.5, v40
	v_add_f32_e32 v76, 1.0, v76
	v_rcp_f32_e32 v76, v76
	s_nop 0
	v_fma_f32 v76, v76, -2.0, 1.0
	v_add_f32_e32 v76, 1.0, v76
	v_mul_f32_e32 v40, v40, v76
	v_or_b32_e32 v76, s9, v82
	v_or_b32_e32 v76, s4, v76
	v_lshlrev_b64 v[104:105], 10, v[76:77]
	v_cvt_pk_bf16_f32 v40, v40, s0
	v_lshl_add_u64 v[104:105], v[72:73], 0, v[104:105]
	global_store_short v[104:105], v40, off
	ds_read_b32 v40, v85
	s_waitcnt lgkmcnt(0)
	v_fma_f32 v40, v102, v40, v41
	v_mul_f32_e32 v41, 0x3d372713, v40
	v_mul_f32_e32 v41, v40, v41
	v_fma_f32 v41, v40, v41, v40
	v_mul_f32_e32 v41, 0x3f4c422a, v41
	v_add_f32_e32 v41, v41, v41
	v_mul_f32_e32 v41, 0x3fb8aa3b, v41
	v_exp_f32_e32 v41, v41
	v_mul_f32_e32 v40, 0.5, v40
	v_add_f32_e32 v41, 1.0, v41
	v_rcp_f32_e32 v41, v41
	s_nop 0
	v_fma_f32 v41, v41, -2.0, 1.0
	v_add_f32_e32 v41, 1.0, v41
	v_mul_f32_e32 v40, v40, v41
	v_cvt_pk_bf16_f32 v103, v40, s0
	v_or_b32_e32 v40, s9, v84
	v_or_b32_e32 v76, s4, v40
	v_lshlrev_b64 v[40:41], 10, v[76:77]
	v_lshl_add_u64 v[40:41], v[72:73], 0, v[40:41]
	global_store_short v[40:41], v103, off
	ds_read_b32 v40, v87
	s_waitcnt lgkmcnt(0)
	v_fma_f32 v40, v102, v40, v42
	v_mul_f32_e32 v41, 0x3d372713, v40
	v_mul_f32_e32 v41, v40, v41
	v_fma_f32 v41, v40, v41, v40
	v_mul_f32_e32 v41, 0x3f4c422a, v41
	v_add_f32_e32 v41, v41, v41
	v_mul_f32_e32 v41, 0x3fb8aa3b, v41
	v_exp_f32_e32 v41, v41
	v_mul_f32_e32 v40, 0.5, v40
	v_add_f32_e32 v41, 1.0, v41
	v_rcp_f32_e32 v41, v41
	s_nop 0
	v_fma_f32 v41, v41, -2.0, 1.0
	v_add_f32_e32 v41, 1.0, v41
	v_mul_f32_e32 v40, v40, v41
	v_cvt_pk_bf16_f32 v42, v40, s0
	v_or_b32_e32 v40, s9, v86
	v_or_b32_e32 v76, s4, v40
	v_lshlrev_b64 v[40:41], 10, v[76:77]
	v_lshl_add_u64 v[40:41], v[72:73], 0, v[40:41]
	global_store_short v[40:41], v42, off
	ds_read_b32 v40, v89
	s_waitcnt lgkmcnt(0)
; __device__ __forceinline__ float ozero() { float z = 0.f; asm volatile("" : "+v"(z)); return z; }
; __device__ __forceinline__ bf f2bf(float f) { return (bf)(pk2(f, 0.f) & 0xFFFFu); }
; __device__ __forceinline__ f32x4 mfma16(bf16x8 a, bf16x8 b, f32x4 c) { return __builtin_amdgcn_mfma_f32_16x16x32_bf16(a, b, c, 0, 0, 0); }
; __device__ __forceinline__ void s5_pass2(const Params& p, int layer, int task, char* sm) {
;     ...
; #pragma unroll
;       for (int mb = 0; mb < 2; mb++) {
;         const float z_ = ozero(); f32x4 acc = {z_, z_, z_, z_};
; #pragma unroll
;         for (int ks = 0; ks < 4; ks++) {
;           bf16x8 af = *(const bf16x8*)(sS + (16 * mb + (lane & 15)) * 136 + ks * 32 + 8 * (lane >> 4));
;           acc = mfma16(af, cf[ks], acc);
;         }
; #pragma unroll
;         for (int r = 0; r < 4; r++) {
;           const int l = 16 * mb + 4 * (lane >> 4) + r;
;           float y = acc[r] + dsk * sU[l * 16 + (lane & 15)];
;           p.YG[(tok0 + sub * 32 + l) * 512 + g * 16 + (lane & 15)] = f2bf(geluf_(y));
;         }
	v_fmac_f32_e32 v43, v102, v40
	v_mul_f32_e32 v40, 0x3d372713, v43
	v_mul_f32_e32 v40, v43, v40
	v_fma_f32 v40, v43, v40, v43
	v_mul_f32_e32 v40, 0x3f4c422a, v40
	v_add_f32_e32 v40, v40, v40
	v_mul_f32_e32 v40, 0x3fb8aa3b, v40
	v_exp_f32_e32 v40, v40
	v_mul_f32_e32 v41, 0.5, v43
	v_add_f32_e32 v40, 1.0, v40
	v_rcp_f32_e32 v40, v40
	s_nop 0
	v_fma_f32 v40, v40, -2.0, 1.0
	v_add_f32_e32 v40, 1.0, v40
	v_mul_f32_e32 v40, v41, v40
	v_cvt_pk_bf16_f32 v42, v40, s0
	v_or_b32_e32 v40, s9, v88
	v_or_b32_e32 v76, s4, v40
	v_lshlrev_b64 v[40:41], 10, v[76:77]
	v_lshl_add_u64 v[40:41], v[72:73], 0, v[40:41]
	global_store_short v[40:41], v42, off
	v_mov_b32_e32 v40, v145
	ds_read_b128 v[104:107], v100 offset:6400
	ds_read_b32 v76, v91
	v_mov_b32_e32 v41, v40
	v_mov_b32_e32 v42, v40
	v_mov_b32_e32 v43, v40
	s_waitcnt lgkmcnt(1)
	s_nop 0
	v_mfma_f32_16x16x32_bf16 v[40:43], v[104:107], v[24:27], v[40:43]
	ds_read_b128 v[104:107], v100 offset:6464
	s_waitcnt lgkmcnt(0)
	v_mfma_f32_16x16x32_bf16 v[40:43], v[104:107], v[28:31], v[40:43]
	ds_read_b128 v[104:107], v100 offset:6528
	s_waitcnt lgkmcnt(0)
	v_mfma_f32_16x16x32_bf16 v[40:43], v[104:107], v[32:35], v[40:43]
	ds_read_b128 v[104:107], v100 offset:6592
	s_waitcnt lgkmcnt(0)
	v_mfma_f32_16x16x32_bf16 v[40:43], v[104:107], v[36:39], v[40:43]
	s_nop 7
	v_fma_f32 v40, v102, v76, v40
	v_mul_f32_e32 v76, 0x3d372713, v40
	v_mul_f32_e32 v76, v40, v76
	v_fma_f32 v76, v40, v76, v40
	v_mul_f32_e32 v76, 0x3f4c422a, v76
	v_add_f32_e32 v76, v76, v76
	v_mul_f32_e32 v76, 0x3fb8aa3b, v76
	v_exp_f32_e32 v76, v76
	v_mul_f32_e32 v40, 0.5, v40
	v_add_f32_e32 v76, 1.0, v76
	v_rcp_f32_e32 v76, v76
	s_nop 0
	v_fma_f32 v76, v76, -2.0, 1.0
	v_add_f32_e32 v76, 1.0, v76
	v_mul_f32_e32 v40, v40, v76
	v_or_b32_e32 v76, s9, v90
	v_or_b32_e32 v76, s4, v76
	v_lshlrev_b64 v[104:105], 10, v[76:77]
	v_cvt_pk_bf16_f32 v40, v40, s0
	v_lshl_add_u64 v[104:105], v[72:73], 0, v[104:105]
	global_store_short v[104:105], v40, off
	ds_read_b32 v40, v93
	s_waitcnt lgkmcnt(0)
	v_fma_f32 v40, v102, v40, v41
	v_mul_f32_e32 v41, 0x3d372713, v40
	v_mul_f32_e32 v41, v40, v41
	v_fma_f32 v41, v40, v41, v40
	v_mul_f32_e32 v41, 0x3f4c422a, v41
	v_add_f32_e32 v41, v41, v41
	v_mul_f32_e32 v41, 0x3fb8aa3b, v41
	v_exp_f32_e32 v41, v41
	v_mul_f32_e32 v40, 0.5, v40
	v_add_f32_e32 v41, 1.0, v41
	v_rcp_f32_e32 v41, v41
	s_nop 0
	v_fma_f32 v41, v41, -2.0, 1.0
	v_add_f32_e32 v41, 1.0, v41
	v_mul_f32_e32 v40, v40, v41
	v_cvt_pk_bf16_f32 v103, v40, s0
	v_or_b32_e32 v40, s9, v92
	v_or_b32_e32 v76, s4, v40
	v_lshlrev_b64 v[40:41], 10, v[76:77]
	v_lshl_add_u64 v[40:41], v[72:73], 0, v[40:41]
	global_store_short v[40:41], v103, off
	ds_read_b32 v40, v95
	s_waitcnt lgkmcnt(0)
	v_fma_f32 v40, v102, v40, v42
	v_mul_f32_e32 v41, 0x3d372713, v40
	v_mul_f32_e32 v41, v40, v41
	v_fma_f32 v41, v40, v41, v40
	v_mul_f32_e32 v41, 0x3f4c422a, v41
	v_add_f32_e32 v41, v41, v41
	v_mul_f32_e32 v41, 0x3fb8aa3b, v41
	v_exp_f32_e32 v41, v41
	v_mul_f32_e32 v40, 0.5, v40
	v_add_f32_e32 v41, 1.0, v41
	v_rcp_f32_e32 v41, v41
	s_nop 0
	v_fma_f32 v41, v41, -2.0, 1.0
	v_add_f32_e32 v41, 1.0, v41
	v_mul_f32_e32 v40, v40, v41
	v_cvt_pk_bf16_f32 v42, v40, s0
	v_or_b32_e32 v40, s9, v94
	v_or_b32_e32 v76, s4, v40
	v_lshlrev_b64 v[40:41], 10, v[76:77]
	v_lshl_add_u64 v[40:41], v[72:73], 0, v[40:41]
	global_store_short v[40:41], v42, off
	ds_read_b32 v40, v97
	s_waitcnt lgkmcnt(0)
	v_fmac_f32_e32 v43, v102, v40
	v_mul_f32_e32 v40, 0x3d372713, v43
	v_mul_f32_e32 v40, v43, v40
	v_fma_f32 v40, v43, v40, v43
	v_mul_f32_e32 v40, 0x3f4c422a, v40
	v_add_f32_e32 v40, v40, v40
	v_mul_f32_e32 v40, 0x3fb8aa3b, v40
	v_exp_f32_e32 v40, v40
	v_mul_f32_e32 v41, 0.5, v43
	v_add_f32_e32 v40, 1.0, v40
	v_rcp_f32_e32 v40, v40
	s_nop 0
	v_fma_f32 v40, v40, -2.0, 1.0
	v_add_f32_e32 v40, 1.0, v40
	v_mul_f32_e32 v40, v41, v40
	v_cvt_pk_bf16_f32 v42, v40, s0
	v_or_b32_e32 v40, s9, v96
	v_or_b32_e32 v76, s4, v40
	v_lshlrev_b64 v[40:41], 10, v[76:77]
	v_lshl_add_u64 v[40:41], v[72:73], 0, v[40:41]
	global_store_short v[40:41], v42, off
	s_cbranch_scc1 .LBB0_1789
	s_mov_b32 s11, s8
	s_branch .LBB0_1791

; __device__ __forceinline__ float ozero() { float z = 0.f; asm volatile("" : "+v"(z)); return z; }
; __device__ __forceinline__ bf f2bf(float f) { return (bf)(pk2(f, 0.f) & 0xFFFFu); }
; __device__ __forceinline__ f32x4 mfma16(bf16x8 a, bf16x8 b, f32x4 c) { return __builtin_amdgcn_mfma_f32_16x16x32_bf16(a, b, c, 0, 0, 0); }
; __device__ __forceinline__ void s5_pass2(const Params& p, int layer, int task, char* sm) {
;     ...
;       for (int l = 0; l < 32; l++) {
;         S5_STEP(sU + l * 16)
;         sS[l * 136 + lane] = f2bf(sr); sS[l * 136 + 64 + lane] = f2bf(si);
;       }
;       __builtin_amdgcn_wave_barrier();
; #pragma unroll
;       for (int mb = 0; mb < 2; mb++) {
;         const float z_ = ozero(); f32x4 acc = {z_, z_, z_, z_};
; #pragma unroll
;         for (int ks = 0; ks < 4; ks++) {
;           bf16x8 af = *(const bf16x8*)(sS + (16 * mb + (lane & 15)) * 136 + ks * 32 + 8 * (lane >> 4));
;           acc = mfma16(af, cf[ks], acc);
;         }
; #pragma unroll
;         for (int r = 0; r < 4; r++) {
;           const int l = 16 * mb + 4 * (lane >> 4) + r;
;           float y = acc[r] + dsk * sU[l * 16 + (lane & 15)];
.Ls5scan_1:
	v_add_u32_e32 v41, s9, v79
	v_add_u32_e32 v103, v79, v40
	s_waitcnt lgkmcnt(10)
	v_pk_mul_f32 v[136:137], v[20:21], v[104:105] op_sel:[0,1]
	v_pk_mul_f32 v[138:139], v[20:21], v[120:121] op_sel:[0,1]
	v_pk_mul_f32 v[76:77], v[74:75], v[70:71] op_sel:[0,1]
	v_pk_fma_f32 v[136:137], v[52:53], v[104:105], v[136:137] op_sel_hi:[1,0,1]
	v_pk_fma_f32 v[138:139], v[52:53], v[120:121], v[138:139] op_sel_hi:[1,0,1]
	v_pk_fma_f32 v[146:147], v[68:69], v[70:71], v[76:77] neg_lo:[0,0,1] neg_hi:[0,0,1]
	v_pk_fma_f32 v[136:137], v[54:55], v[106:107], v[136:137] op_sel_hi:[1,0,1]
	v_pk_fma_f32 v[138:139], v[54:55], v[122:123], v[138:139] op_sel_hi:[1,0,1]
	v_pk_fma_f32 v[148:149], v[68:69], v[70:71], v[76:77] op_sel_hi:[1,0,1]
	v_pk_fma_f32 v[136:137], v[22:23], v[106:107], v[136:137] op_sel:[0,1,0]
	v_pk_fma_f32 v[138:139], v[22:23], v[122:123], v[138:139] op_sel:[0,1,0]
	v_mov_b32_e32 v147, v149
	ds_read_b128 v[104:107], v41 offset:256
	ds_read_b128 v[120:123], v41 offset:320
	s_waitcnt lgkmcnt(8)
	v_pk_fma_f32 v[136:137], v[56:57], v[108:109], v[136:137] op_sel_hi:[1,0,1]
	v_pk_fma_f32 v[138:139], v[56:57], v[124:125], v[138:139] op_sel_hi:[1,0,1]
	v_pk_add_f32 v[42:43], v[146:147], v[140:141]
	v_pk_fma_f32 v[136:137], v[16:17], v[108:109], v[136:137] op_sel:[0,1,0]
	v_pk_fma_f32 v[138:139], v[16:17], v[124:125], v[138:139] op_sel:[0,1,0]
	v_cvt_pk_bf16_f32 v150, v42, s0
	ds_write_b16 v103, v150
	v_pk_fma_f32 v[136:137], v[58:59], v[110:111], v[136:137] op_sel_hi:[1,0,1]
	v_pk_fma_f32 v[138:139], v[58:59], v[126:127], v[138:139] op_sel_hi:[1,0,1]
	v_cvt_pk_bf16_f32 v151, v43, s0
	ds_write_b16 v103, v151 offset:128
	v_pk_fma_f32 v[136:137], v[18:19], v[110:111], v[136:137] op_sel:[0,1,0]
	v_pk_fma_f32 v[138:139], v[18:19], v[126:127], v[138:139] op_sel:[0,1,0]
	v_pk_mul_f32 v[76:77], v[74:75], v[42:43] op_sel:[0,1]
	ds_read_b128 v[108:111], v41 offset:272
	ds_read_b128 v[124:127], v41 offset:336
	s_waitcnt lgkmcnt(10)
	v_pk_fma_f32 v[136:137], v[60:61], v[112:113], v[136:137] op_sel_hi:[1,0,1]
	v_pk_fma_f32 v[138:139], v[60:61], v[128:129], v[138:139] op_sel_hi:[1,0,1]
	v_pk_fma_f32 v[146:147], v[68:69], v[42:43], v[76:77] neg_lo:[0,0,1] neg_hi:[0,0,1]
	v_pk_fma_f32 v[136:137], v[12:13], v[112:113], v[136:137] op_sel:[0,1,0]
	v_pk_fma_f32 v[138:139], v[12:13], v[128:129], v[138:139] op_sel:[0,1,0]
	v_pk_fma_f32 v[148:149], v[68:69], v[42:43], v[76:77] op_sel_hi:[1,0,1]
	v_pk_fma_f32 v[136:137], v[62:63], v[114:115], v[136:137] op_sel_hi:[1,0,1]
	v_pk_fma_f32 v[138:139], v[62:63], v[130:131], v[138:139] op_sel_hi:[1,0,1]
	v_mov_b32_e32 v147, v149
	v_pk_fma_f32 v[136:137], v[14:15], v[114:115], v[136:137] op_sel:[0,1,0]
	v_pk_fma_f32 v[138:139], v[14:15], v[130:131], v[138:139] op_sel:[0,1,0]
	v_pk_add_f32 v[70:71], v[146:147], v[142:143]
	ds_read_b128 v[112:115], v41 offset:288
	ds_read_b128 v[128:131], v41 offset:352
	s_waitcnt lgkmcnt(8)
	v_pk_fma_f32 v[136:137], v[64:65], v[116:117], v[136:137] op_sel_hi:[1,0,1]
	v_pk_fma_f32 v[138:139], v[64:65], v[132:133], v[138:139] op_sel_hi:[1,0,1]
	v_cvt_pk_bf16_f32 v150, v70, s0
	ds_write_b16 v103, v150 offset:272
	v_pk_fma_f32 v[136:137], v[8:9], v[116:117], v[136:137] op_sel:[0,1,0]
	v_pk_fma_f32 v[138:139], v[8:9], v[132:133], v[138:139] op_sel:[0,1,0]
	v_cvt_pk_bf16_f32 v151, v71, s0
	ds_write_b16 v103, v151 offset:400
	v_pk_fma_f32 v[136:137], v[66:67], v[118:119], v[136:137] op_sel_hi:[1,0,1]
	v_pk_fma_f32 v[138:139], v[66:67], v[134:135], v[138:139] op_sel_hi:[1,0,1]
	v_pk_fma_f32 v[136:137], v[10:11], v[118:119], v[136:137] op_sel:[0,1,0]
	v_pk_fma_f32 v[138:139], v[10:11], v[134:135], v[138:139] op_sel:[0,1,0]
	ds_read_b128 v[116:119], v41 offset:304
	ds_read_b128 v[132:135], v41 offset:368
	s_addk_i32 s9, 0x80
	v_add_u32_e32 v40, 0x220, v40
	v_mov_b64_e32 v[140:141], v[136:137]
	v_mov_b64_e32 v[142:143], v[138:139]
	s_cmpk_eq_i32 s9, 0x780
	s_cbranch_scc0 .Ls5scan_1
	v_add_u32_e32 v103, v79, v40
	v_pk_mul_f32 v[76:77], v[74:75], v[70:71] op_sel:[0,1]
	s_nop 0
	v_pk_fma_f32 v[146:147], v[68:69], v[70:71], v[76:77] neg_lo:[0,0,1] neg_hi:[0,0,1]
	s_nop 0
	v_pk_fma_f32 v[148:149], v[68:69], v[70:71], v[76:77] op_sel_hi:[1,0,1]
	s_nop 0
	v_mov_b32_e32 v147, v149
	s_nop 0
	v_pk_add_f32 v[42:43], v[146:147], v[140:141]
	s_nop 0
	v_cvt_pk_bf16_f32 v150, v42, s0
	s_nop 0
	ds_write_b16 v103, v150
	v_cvt_pk_bf16_f32 v151, v43, s0
	s_nop 0
	ds_write_b16 v103, v151 offset:128
	v_pk_mul_f32 v[76:77], v[74:75], v[42:43] op_sel:[0,1]
	s_nop 0
	v_pk_fma_f32 v[146:147], v[68:69], v[42:43], v[76:77] neg_lo:[0,0,1] neg_hi:[0,0,1]
	s_nop 0
	v_pk_fma_f32 v[148:149], v[68:69], v[42:43], v[76:77] op_sel_hi:[1,0,1]
	s_nop 0
	v_mov_b32_e32 v147, v149
	s_nop 0
	v_pk_add_f32 v[70:71], v[146:147], v[142:143]
	s_nop 0
	v_cvt_pk_bf16_f32 v150, v70, s0
	s_nop 0
	ds_write_b16 v103, v150 offset:272
	v_cvt_pk_bf16_f32 v151, v71, s0
	s_nop 0
	ds_write_b16 v103, v151 offset:400
	s_waitcnt lgkmcnt(0)
	v_mov_b32_e32 v40, v145
	ds_read_b128 v[104:107], v100 offset:2048
	ds_read_b32 v76, v83
	v_mov_b32_e32 v41, v40
	v_mov_b32_e32 v42, v40
	v_mov_b32_e32 v43, v40
	s_lshl_b32 s9, s12, 5
	v_mov_b32_e32 v77, s5
	s_cmp_eq_u32 s8, 4
	s_waitcnt vmcnt(4) lgkmcnt(1)
	v_mfma_f32_16x16x32_bf16 v[40:43], v[104:107], v[24:27], v[40:43]
	ds_read_b128 v[104:107], v100 offset:2112
	s_waitcnt vmcnt(3) lgkmcnt(0)
	v_mfma_f32_16x16x32_bf16 v[40:43], v[104:107], v[28:31], v[40:43]
	ds_read_b128 v[104:107], v100 offset:2176
	s_waitcnt vmcnt(2) lgkmcnt(0)
	v_mfma_f32_16x16x32_bf16 v[40:43], v[104:107], v[32:35], v[40:43]
	ds_read_b128 v[104:107], v100 offset:2240
	s_waitcnt vmcnt(1) lgkmcnt(0)
	v_mfma_f32_16x16x32_bf16 v[40:43], v[104:107], v[36:39], v[40:43]
	s_waitcnt vmcnt(0)
; __device__ __forceinline__ float ozero() { float z = 0.f; asm volatile("" : "+v"(z)); return z; }
; __device__ __forceinline__ bf f2bf(float f) { return (bf)(pk2(f, 0.f) & 0xFFFFu); }
; __device__ __forceinline__ f32x4 mfma16(bf16x8 a, bf16x8 b, f32x4 c) { return __builtin_amdgcn_mfma_f32_16x16x32_bf16(a, b, c, 0, 0, 0); }
; __device__ __forceinline__ void s5_pass2(const Params& p, int layer, int task, char* sm) {
;     ...
; #pragma unroll
;       for (int mb = 0; mb < 2; mb++) {
;         const float z_ = ozero(); f32x4 acc = {z_, z_, z_, z_};
; #pragma unroll
;         for (int ks = 0; ks < 4; ks++) {
;           bf16x8 af = *(const bf16x8*)(sS + (16 * mb + (lane & 15)) * 136 + ks * 32 + 8 * (lane >> 4));
;           acc = mfma16(af, cf[ks], acc);
;         }
; #pragma unroll
;         for (int r = 0; r < 4; r++) {
;           const int l = 16 * mb + 4 * (lane >> 4) + r;
;           float y = acc[r] + dsk * sU[l * 16 + (lane & 15)];
;           p.YG[(tok0 + sub * 32 + l) * 512 + g * 16 + (lane & 15)] = f2bf(geluf_(y));
;         }
	s_nop 6
	v_fma_f32 v40, v102, v76, v40
	v_mul_f32_e32 v76, 0x3d372713, v40
	v_mul_f32_e32 v76, v40, v76
	v_fma_f32 v76, v40, v76, v40
	v_mul_f32_e32 v76, 0x3f4c422a, v76
	v_add_f32_e32 v76, v76, v76
	v_mul_f32_e32 v76, 0x3fb8aa3b, v76
	v_exp_f32_e32 v76, v76
	v_mul_f32_e32 v40, 0.5, v40
	v_add_f32_e32 v76, 1.0, v76
	v_rcp_f32_e32 v76, v76
	s_nop 0
	v_fma_f32 v76, v76, -2.0, 1.0
	v_add_f32_e32 v76, 1.0, v76
	v_mul_f32_e32 v40, v40, v76
	v_or_b32_e32 v76, s9, v82
	v_or_b32_e32 v76, s4, v76
	v_lshlrev_b64 v[104:105], 10, v[76:77]
	v_cvt_pk_bf16_f32 v40, v40, s0
	v_lshl_add_u64 v[104:105], v[72:73], 0, v[104:105]
	global_store_short v[104:105], v40, off
	ds_read_b32 v40, v85
	s_waitcnt lgkmcnt(0)
	v_fma_f32 v40, v102, v40, v41
	v_mul_f32_e32 v41, 0x3d372713, v40
	v_mul_f32_e32 v41, v40, v41
	v_fma_f32 v41, v40, v41, v40
	v_mul_f32_e32 v41, 0x3f4c422a, v41
	v_add_f32_e32 v41, v41, v41
	v_mul_f32_e32 v41, 0x3fb8aa3b, v41
	v_exp_f32_e32 v41, v41
	v_mul_f32_e32 v40, 0.5, v40
	v_add_f32_e32 v41, 1.0, v41
	v_rcp_f32_e32 v41, v41
	s_nop 0
	v_fma_f32 v41, v41, -2.0, 1.0
	v_add_f32_e32 v41, 1.0, v41
	v_mul_f32_e32 v40, v40, v41
	v_cvt_pk_bf16_f32 v103, v40, s0
	v_or_b32_e32 v40, s9, v84
	v_or_b32_e32 v76, s4, v40
	v_lshlrev_b64 v[40:41], 10, v[76:77]
	v_lshl_add_u64 v[40:41], v[72:73], 0, v[40:41]
	global_store_short v[40:41], v103, off
	ds_read_b32 v40, v87
	s_waitcnt lgkmcnt(0)
	v_fma_f32 v40, v102, v40, v42
	v_mul_f32_e32 v41, 0x3d372713, v40
	v_mul_f32_e32 v41, v40, v41
	v_fma_f32 v41, v40, v41, v40
	v_mul_f32_e32 v41, 0x3f4c422a, v41
	v_add_f32_e32 v41, v41, v41
	v_mul_f32_e32 v41, 0x3fb8aa3b, v41
	v_exp_f32_e32 v41, v41
	v_mul_f32_e32 v40, 0.5, v40
	v_add_f32_e32 v41, 1.0, v41
	v_rcp_f32_e32 v41, v41
	s_nop 0
	v_fma_f32 v41, v41, -2.0, 1.0
	v_add_f32_e32 v41, 1.0, v41
	v_mul_f32_e32 v40, v40, v41
	v_cvt_pk_bf16_f32 v42, v40, s0
	v_or_b32_e32 v40, s9, v86
	v_or_b32_e32 v76, s4, v40
	v_lshlrev_b64 v[40:41], 10, v[76:77]
	v_lshl_add_u64 v[40:41], v[72:73], 0, v[40:41]
	global_store_short v[40:41], v42, off
	ds_read_b32 v40, v89
	s_waitcnt lgkmcnt(0)
	v_fmac_f32_e32 v43, v102, v40
	v_mul_f32_e32 v40, 0x3d372713, v43
	v_mul_f32_e32 v40, v43, v40
	v_fma_f32 v40, v43, v40, v43
	v_mul_f32_e32 v40, 0x3f4c422a, v40
	v_add_f32_e32 v40, v40, v40
	v_mul_f32_e32 v40, 0x3fb8aa3b, v40
	v_exp_f32_e32 v40, v40
	v_mul_f32_e32 v41, 0.5, v43
	v_add_f32_e32 v40, 1.0, v40
	v_rcp_f32_e32 v40, v40
	s_nop 0
	v_fma_f32 v40, v40, -2.0, 1.0
	v_add_f32_e32 v40, 1.0, v40
	v_mul_f32_e32 v40, v41, v40
	v_cvt_pk_bf16_f32 v42, v40, s0
	v_or_b32_e32 v40, s9, v88
	v_or_b32_e32 v76, s4, v40
	v_lshlrev_b64 v[40:41], 10, v[76:77]
	v_lshl_add_u64 v[40:41], v[72:73], 0, v[40:41]
	global_store_short v[40:41], v42, off
	v_mov_b32_e32 v40, v145
	ds_read_b128 v[104:107], v100 offset:6400
	ds_read_b32 v76, v91
	v_mov_b32_e32 v41, v40
	v_mov_b32_e32 v42, v40
	v_mov_b32_e32 v43, v40
	s_waitcnt lgkmcnt(1)
	s_nop 0
	v_mfma_f32_16x16x32_bf16 v[40:43], v[104:107], v[24:27], v[40:43]
	ds_read_b128 v[104:107], v100 offset:6464
	s_waitcnt lgkmcnt(0)
	v_mfma_f32_16x16x32_bf16 v[40:43], v[104:107], v[28:31], v[40:43]
	ds_read_b128 v[104:107], v100 offset:6528
	s_waitcnt lgkmcnt(0)
	v_mfma_f32_16x16x32_bf16 v[40:43], v[104:107], v[32:35], v[40:43]
	ds_read_b128 v[104:107], v100 offset:6592
	s_waitcnt lgkmcnt(0)
	v_mfma_f32_16x16x32_bf16 v[40:43], v[104:107], v[36:39], v[40:43]
	s_nop 7
	v_fma_f32 v40, v102, v76, v40
	v_mul_f32_e32 v76, 0x3d372713, v40
	v_mul_f32_e32 v76, v40, v76
	v_fma_f32 v76, v40, v76, v40
	v_mul_f32_e32 v76, 0x3f4c422a, v76
	v_add_f32_e32 v76, v76, v76
	v_mul_f32_e32 v76, 0x3fb8aa3b, v76
	v_exp_f32_e32 v76, v76
	v_mul_f32_e32 v40, 0.5, v40
	v_add_f32_e32 v76, 1.0, v76
	v_rcp_f32_e32 v76, v76
	s_nop 0
	v_fma_f32 v76, v76, -2.0, 1.0
	v_add_f32_e32 v76, 1.0, v76
	v_mul_f32_e32 v40, v40, v76
	v_or_b32_e32 v76, s9, v90
	v_or_b32_e32 v76, s4, v76
	v_lshlrev_b64 v[104:105], 10, v[76:77]
	v_cvt_pk_bf16_f32 v40, v40, s0
	v_lshl_add_u64 v[104:105], v[72:73], 0, v[104:105]
	global_store_short v[104:105], v40, off
	ds_read_b32 v40, v93
	s_waitcnt lgkmcnt(0)
	v_fma_f32 v40, v102, v40, v41
	v_mul_f32_e32 v41, 0x3d372713, v40
	v_mul_f32_e32 v41, v40, v41
	v_fma_f32 v41, v40, v41, v40
	v_mul_f32_e32 v41, 0x3f4c422a, v41
	v_add_f32_e32 v41, v41, v41
	v_mul_f32_e32 v41, 0x3fb8aa3b, v41
	v_exp_f32_e32 v41, v41
	v_mul_f32_e32 v40, 0.5, v40
	v_add_f32_e32 v41, 1.0, v41
	v_rcp_f32_e32 v41, v41
	s_nop 0
	v_fma_f32 v41, v41, -2.0, 1.0
	v_add_f32_e32 v41, 1.0, v41
	v_mul_f32_e32 v40, v40, v41
	v_cvt_pk_bf16_f32 v103, v40, s0
	v_or_b32_e32 v40, s9, v92
	v_or_b32_e32 v76, s4, v40
	v_lshlrev_b64 v[40:41], 10, v[76:77]
	v_lshl_add_u64 v[40:41], v[72:73], 0, v[40:41]
	global_store_short v[40:41], v103, off
	ds_read_b32 v40, v95
	s_waitcnt lgkmcnt(0)
	v_fma_f32 v40, v102, v40, v42
	v_mul_f32_e32 v41, 0x3d372713, v40
	v_mul_f32_e32 v41, v40, v41
	v_fma_f32 v41, v40, v41, v40
	v_mul_f32_e32 v41, 0x3f4c422a, v41
	v_add_f32_e32 v41, v41, v41
	v_mul_f32_e32 v41, 0x3fb8aa3b, v41
	v_exp_f32_e32 v41, v41
	v_mul_f32_e32 v40, 0.5, v40
	v_add_f32_e32 v41, 1.0, v41
	v_rcp_f32_e32 v41, v41
	s_nop 0
	v_fma_f32 v41, v41, -2.0, 1.0
	v_add_f32_e32 v41, 1.0, v41
	v_mul_f32_e32 v40, v40, v41
	v_cvt_pk_bf16_f32 v42, v40, s0
	v_or_b32_e32 v40, s9, v94
	v_or_b32_e32 v76, s4, v40
	v_lshlrev_b64 v[40:41], 10, v[76:77]
	v_lshl_add_u64 v[40:41], v[72:73], 0, v[40:41]
	global_store_short v[40:41], v42, off
	ds_read_b32 v40, v97
	s_waitcnt lgkmcnt(0)
	v_fmac_f32_e32 v43, v102, v40
	v_mul_f32_e32 v40, 0x3d372713, v43
	v_mul_f32_e32 v40, v43, v40
	v_fma_f32 v40, v43, v40, v43
	v_mul_f32_e32 v40, 0x3f4c422a, v40
	v_add_f32_e32 v40, v40, v40
	v_mul_f32_e32 v40, 0x3fb8aa3b, v40
	v_exp_f32_e32 v40, v40
	v_mul_f32_e32 v41, 0.5, v43
	v_add_f32_e32 v40, 1.0, v40
	v_rcp_f32_e32 v40, v40
	s_nop 0
	v_fma_f32 v40, v40, -2.0, 1.0
	v_add_f32_e32 v40, 1.0, v40
	v_mul_f32_e32 v40, v41, v40
	v_cvt_pk_bf16_f32 v42, v40, s0
	v_or_b32_e32 v40, s9, v96
	v_or_b32_e32 v76, s4, v40
	v_lshlrev_b64 v[40:41], 10, v[76:77]
	v_lshl_add_u64 v[40:41], v[72:73], 0, v[40:41]
	global_store_short v[40:41], v42, off
	s_cbranch_scc1 .LBB0_2053
	s_mov_b32 s12, s8
	s_branch .LBB0_2055
